# merged-GEMM (P3) epilogue: gate tiles prefetched through a 7-slot register ring instead of one wait per chunk
# speedup vs baseline: 1.0463x; 1.0463x over previous
.LBB0_446:
	v_mov_b32_e32 v128, v155
	v_mov_b32_e32 v129, v156
	s_add_i32 s12, s88, s66
	v_add_u32_e32 v128, s12, v128
	v_mov_b64_e32 v[132:133], s[8:9]
	v_mad_i64_i32 v[132:133], s[40:41], v128, s70, v[132:133]
	s_lshl_b32 s12, s87, 1
	s_and_b32 s40, s12, 0xffffff00
	v_lshl_add_u32 v130, v129, 3, s67
	s_ashr_i32 s41, s40, 31
	v_lshl_add_u64 v[132:133], s[40:41], 1, v[132:133]
	v_ashrrev_i32_e32 v131, 31, v130
	v_lshl_add_u64 v[132:133], v[130:131], 1, v[132:133]
	v_add_co_u32_e32 v134, vcc, s65, v132
	v_ashrrev_i32_e32 v129, 31, v128
	s_nop 0
	v_addc_co_u32_e32 v135, vcc, 0, v133, vcc
	flat_load_dwordx4 v[134:137], v[134:135] offset:2304
	v_add_u32_e32 v130, s87, v130
	v_lshlrev_b64 v[138:139], 12, v[128:129]
	v_ashrrev_i32_e32 v131, 31, v130
	v_lshl_add_u64 v[138:139], s[10:11], 0, v[138:139]
	v_lshlrev_b64 v[130:131], 1, v[130:131]
	v_lshl_add_u64 v[138:139], v[138:139], 0, v[130:131]
	v_lshl_add_u64 v[152:153], v[132:133], 0, s[44:45]
	s_waitcnt vmcnt(0) lgkmcnt(0)
	global_load_dwordx4 v[232:235], v[152:153], off offset:512
	v_add_co_u32_e32 v198, vcc, s71, v132
	s_nop 1
	v_addc_co_u32_e32 v199, vcc, 0, v133, vcc
	global_load_dwordx4 v[236:239], v[198:199], off offset:2304
	v_add_co_u32_e32 v198, vcc, s71, v132
	s_nop 1
	v_addc_co_u32_e32 v199, vcc, 0, v133, vcc
	global_load_dwordx4 v[240:243], v[198:199], off offset:2816
	v_add_co_u32_e32 v198, vcc, s72, v132
	s_nop 1
	v_addc_co_u32_e32 v199, vcc, 0, v133, vcc
	global_load_dwordx4 v[244:247], v[198:199], off offset:2304
	v_add_co_u32_e32 v198, vcc, s72, v132
	s_nop 1
	v_addc_co_u32_e32 v199, vcc, 0, v133, vcc
	global_load_dwordx4 v[248:251], v[198:199], off offset:2816
	v_add_co_u32_e32 v198, vcc, s73, v132
	s_nop 1
	v_addc_co_u32_e32 v199, vcc, 0, v133, vcc
	global_load_dwordx4 v[252:255], v[198:199], off offset:2304
	v_add_co_u32_e32 v198, vcc, s73, v132
	s_nop 1
	v_addc_co_u32_e32 v199, vcc, 0, v133, vcc
	global_load_dwordx4 v[228:231], v[198:199], off offset:2816
	v_lshlrev_b32_e32 v161, 16, v137
	v_and_b32_e32 v137, 0xffff0000, v137
	v_lshlrev_b32_e32 v129, 16, v134
	v_and_b32_e32 v134, 0xffff0000, v134
	v_lshlrev_b32_e32 v159, 16, v135
	v_and_b32_e32 v135, 0xffff0000, v135
	v_lshlrev_b32_e32 v160, 16, v136
	v_and_b32_e32 v136, 0xffff0000, v136
	v_mul_f32_e32 v123, v123, v137
	v_mul_f32_e32 v124, v124, v129
	v_mul_f32_e32 v125, v125, v134
	v_mul_f32_e32 v126, v126, v159
	v_mul_f32_e32 v127, v127, v135
	v_mul_f32_e32 v129, v120, v160
	v_mul_f32_e32 v134, v121, v136
	v_mul_f32_e32 v135, v122, v161
	v_cvt_pk_bf16_f32 v120, v124, v125
	v_cvt_pk_bf16_f32 v121, v126, v127
	v_cvt_pk_bf16_f32 v122, v129, v134
	v_cvt_pk_bf16_f32 v123, v135, v123
	flat_store_dwordx4 v[138:139], v[120:123]
	v_add_co_u32_e32 v124, vcc, s71, v132
	s_waitcnt vmcnt(7) lgkmcnt(0)
	s_nop 1
	v_mov_b32_e32 v120, v232
	v_mov_b32_e32 v121, v233
	v_mov_b32_e32 v122, v234
	v_mov_b32_e32 v123, v235
	v_lshlrev_b32_e32 v134, 16, v123
	v_and_b32_e32 v123, 0xffff0000, v123
	v_lshlrev_b32_e32 v126, 16, v120
	v_and_b32_e32 v120, 0xffff0000, v120
	v_lshlrev_b32_e32 v127, 16, v121
	v_and_b32_e32 v121, 0xffff0000, v121
	v_lshlrev_b32_e32 v129, 16, v122
	v_and_b32_e32 v122, 0xffff0000, v122
	v_mul_f32_e32 v115, v115, v123
	v_addc_co_u32_e32 v125, vcc, 0, v133, vcc
	v_add_co_u32_e32 v198, vcc, s74, v132
	s_nop 1
	v_addc_co_u32_e32 v199, vcc, 0, v133, vcc
	global_load_dwordx4 v[232:235], v[198:199], off offset:2304
	v_mul_f32_e32 v116, v116, v126
	v_mul_f32_e32 v117, v117, v120
	v_mul_f32_e32 v118, v118, v127
	v_mul_f32_e32 v119, v119, v121
	v_mul_f32_e32 v120, v112, v129
	v_mul_f32_e32 v121, v113, v122
	v_mul_f32_e32 v122, v114, v134
	v_cvt_pk_bf16_f32 v112, v116, v117
	v_cvt_pk_bf16_f32 v113, v118, v119
	v_cvt_pk_bf16_f32 v114, v120, v121
	v_cvt_pk_bf16_f32 v115, v122, v115
	flat_store_dwordx4 v[138:139], v[112:115] offset:256
	v_add_u32_e32 v116, 16, v128
	v_ashrrev_i32_e32 v117, 31, v116
	v_lshlrev_b64 v[116:117], 12, v[116:117]
	v_lshl_add_u64 v[116:117], s[10:11], 0, v[116:117]
	v_lshl_add_u64 v[116:117], v[116:117], 0, v[130:131]
	s_waitcnt vmcnt(8) lgkmcnt(0)
	s_nop 1
	v_mov_b32_e32 v112, v236
	v_mov_b32_e32 v113, v237
	v_mov_b32_e32 v114, v238
	v_mov_b32_e32 v115, v239
	v_add_co_u32_e32 v198, vcc, s74, v132
	s_nop 1
	v_addc_co_u32_e32 v199, vcc, 0, v133, vcc
	global_load_dwordx4 v[236:239], v[198:199], off offset:2816
	v_lshlrev_b32_e32 v121, 16, v115
	v_and_b32_e32 v115, 0xffff0000, v115
	v_lshlrev_b32_e32 v118, 16, v112
	v_and_b32_e32 v112, 0xffff0000, v112
	v_lshlrev_b32_e32 v119, 16, v113
	v_and_b32_e32 v113, 0xffff0000, v113
	v_lshlrev_b32_e32 v120, 16, v114
	v_and_b32_e32 v114, 0xffff0000, v114
	v_mul_f32_e32 v107, v107, v115
	v_mul_f32_e32 v108, v108, v118
	v_mul_f32_e32 v109, v109, v112
	v_mul_f32_e32 v110, v110, v119
	v_mul_f32_e32 v111, v111, v113
	v_mul_f32_e32 v112, v104, v120
	v_mul_f32_e32 v113, v105, v114
	v_mul_f32_e32 v114, v106, v121
	v_cvt_pk_bf16_f32 v104, v108, v109
	v_cvt_pk_bf16_f32 v105, v110, v111
	v_cvt_pk_bf16_f32 v106, v112, v113
	v_cvt_pk_bf16_f32 v107, v114, v107
	flat_store_dwordx4 v[116:117], v[104:107]
	v_add_co_u32_e32 v108, vcc, s72, v132
	s_waitcnt vmcnt(9) lgkmcnt(0)
	s_nop 1
	v_mov_b32_e32 v104, v240
	v_mov_b32_e32 v105, v241
	v_mov_b32_e32 v106, v242
	v_mov_b32_e32 v107, v243
	v_lshlrev_b32_e32 v113, 16, v107
	v_and_b32_e32 v107, 0xffff0000, v107
	v_lshlrev_b32_e32 v110, 16, v104
	v_and_b32_e32 v104, 0xffff0000, v104
	v_lshlrev_b32_e32 v111, 16, v105
	v_and_b32_e32 v105, 0xffff0000, v105
	v_lshlrev_b32_e32 v112, 16, v106
	v_and_b32_e32 v106, 0xffff0000, v106
	v_mul_f32_e32 v99, v99, v107
	v_addc_co_u32_e32 v109, vcc, 0, v133, vcc
	v_add_co_u32_e32 v198, vcc, s75, v132
	s_nop 1
	v_addc_co_u32_e32 v199, vcc, 0, v133, vcc
	global_load_dwordx4 v[240:243], v[198:199], off offset:2304
	v_mul_f32_e32 v100, v100, v110
	v_mul_f32_e32 v101, v101, v104
	v_mul_f32_e32 v102, v102, v111
	v_mul_f32_e32 v103, v103, v105
	v_mul_f32_e32 v104, v96, v112
	v_mul_f32_e32 v105, v97, v106
	v_mul_f32_e32 v106, v98, v113
	v_cvt_pk_bf16_f32 v96, v100, v101
	v_cvt_pk_bf16_f32 v97, v102, v103
	v_cvt_pk_bf16_f32 v98, v104, v105
	v_cvt_pk_bf16_f32 v99, v106, v99
	flat_store_dwordx4 v[116:117], v[96:99] offset:256
	v_add_u32_e32 v100, 32, v128
	v_ashrrev_i32_e32 v101, 31, v100
	v_lshlrev_b64 v[100:101], 12, v[100:101]
	v_lshl_add_u64 v[100:101], s[10:11], 0, v[100:101]
	v_lshl_add_u64 v[100:101], v[100:101], 0, v[130:131]
	s_waitcnt vmcnt(10) lgkmcnt(0)
	s_nop 1
	v_mov_b32_e32 v96, v244
	v_mov_b32_e32 v97, v245
	v_mov_b32_e32 v98, v246
	v_mov_b32_e32 v99, v247
	v_add_co_u32_e32 v198, vcc, s75, v132
	s_nop 1
	v_addc_co_u32_e32 v199, vcc, 0, v133, vcc
	global_load_dwordx4 v[244:247], v[198:199], off offset:2816
	v_lshlrev_b32_e32 v105, 16, v99
	v_and_b32_e32 v99, 0xffff0000, v99
	v_lshlrev_b32_e32 v102, 16, v96
	v_and_b32_e32 v96, 0xffff0000, v96
	v_lshlrev_b32_e32 v103, 16, v97
	v_and_b32_e32 v97, 0xffff0000, v97
	v_lshlrev_b32_e32 v104, 16, v98
	v_and_b32_e32 v98, 0xffff0000, v98
	v_mul_f32_e32 v91, v91, v99
	v_mul_f32_e32 v92, v92, v102
	v_mul_f32_e32 v93, v93, v96
	v_mul_f32_e32 v94, v94, v103
	v_mul_f32_e32 v95, v95, v97
	v_mul_f32_e32 v96, v88, v104
	v_mul_f32_e32 v97, v89, v98
	v_mul_f32_e32 v98, v90, v105
	v_cvt_pk_bf16_f32 v88, v92, v93
	v_cvt_pk_bf16_f32 v89, v94, v95
	v_cvt_pk_bf16_f32 v90, v96, v97
	v_cvt_pk_bf16_f32 v91, v98, v91
	flat_store_dwordx4 v[100:101], v[88:91]
	v_add_co_u32_e32 v92, vcc, s73, v132
	s_waitcnt vmcnt(11) lgkmcnt(0)
	s_nop 1
	v_mov_b32_e32 v88, v248
	v_mov_b32_e32 v89, v249
	v_mov_b32_e32 v90, v250
	v_mov_b32_e32 v91, v251
	v_lshlrev_b32_e32 v97, 16, v91
	v_and_b32_e32 v91, 0xffff0000, v91
	v_lshlrev_b32_e32 v94, 16, v88
	v_and_b32_e32 v88, 0xffff0000, v88
	v_lshlrev_b32_e32 v95, 16, v89
	v_and_b32_e32 v89, 0xffff0000, v89
	v_lshlrev_b32_e32 v96, 16, v90
	v_and_b32_e32 v90, 0xffff0000, v90
	v_mul_f32_e32 v83, v83, v91
	v_addc_co_u32_e32 v93, vcc, 0, v133, vcc
	v_add_co_u32_e32 v198, vcc, s76, v132
	s_nop 1
	v_addc_co_u32_e32 v199, vcc, 0, v133, vcc
	global_load_dwordx4 v[248:251], v[198:199], off offset:2304
	v_mul_f32_e32 v84, v84, v94
	v_mul_f32_e32 v85, v85, v88
	v_mul_f32_e32 v86, v86, v95
	v_mul_f32_e32 v87, v87, v89
	v_mul_f32_e32 v88, v80, v96
	v_mul_f32_e32 v89, v81, v90
	v_mul_f32_e32 v90, v82, v97
	v_cvt_pk_bf16_f32 v80, v84, v85
	v_cvt_pk_bf16_f32 v81, v86, v87
	v_cvt_pk_bf16_f32 v82, v88, v89
	v_cvt_pk_bf16_f32 v83, v90, v83
	flat_store_dwordx4 v[100:101], v[80:83] offset:256
	v_add_u32_e32 v84, 48, v128
	v_ashrrev_i32_e32 v85, 31, v84
	v_lshlrev_b64 v[84:85], 12, v[84:85]
	v_lshl_add_u64 v[84:85], s[10:11], 0, v[84:85]
	v_lshl_add_u64 v[84:85], v[84:85], 0, v[130:131]
	s_waitcnt vmcnt(12) lgkmcnt(0)
	s_nop 1
	v_mov_b32_e32 v80, v252
	v_mov_b32_e32 v81, v253
	v_mov_b32_e32 v82, v254
	v_mov_b32_e32 v83, v255
	v_add_co_u32_e32 v198, vcc, s76, v132
	s_nop 1
	v_addc_co_u32_e32 v199, vcc, 0, v133, vcc
	global_load_dwordx4 v[252:255], v[198:199], off offset:2816
	v_lshlrev_b32_e32 v89, 16, v83
	v_and_b32_e32 v83, 0xffff0000, v83
	v_lshlrev_b32_e32 v86, 16, v80
	v_and_b32_e32 v80, 0xffff0000, v80
	v_lshlrev_b32_e32 v87, 16, v81
	v_and_b32_e32 v81, 0xffff0000, v81
	v_lshlrev_b32_e32 v88, 16, v82
	v_and_b32_e32 v82, 0xffff0000, v82
	v_mul_f32_e32 v75, v75, v83
	v_mul_f32_e32 v76, v76, v86
	v_mul_f32_e32 v77, v77, v80
	v_mul_f32_e32 v78, v78, v87
	v_mul_f32_e32 v79, v79, v81
	v_mul_f32_e32 v80, v72, v88
	v_mul_f32_e32 v81, v73, v82
	v_mul_f32_e32 v82, v74, v89
	v_cvt_pk_bf16_f32 v72, v76, v77
	v_cvt_pk_bf16_f32 v73, v78, v79
	v_cvt_pk_bf16_f32 v74, v80, v81
	v_cvt_pk_bf16_f32 v75, v82, v75
	flat_store_dwordx4 v[84:85], v[72:75]
	v_add_co_u32_e32 v76, vcc, s74, v132
	s_waitcnt vmcnt(13) lgkmcnt(0)
	s_nop 1
	v_mov_b32_e32 v72, v228
	v_mov_b32_e32 v73, v229
	v_mov_b32_e32 v74, v230
	v_mov_b32_e32 v75, v231
	v_lshlrev_b32_e32 v81, 16, v75
	v_and_b32_e32 v75, 0xffff0000, v75
	v_lshlrev_b32_e32 v78, 16, v72
	v_and_b32_e32 v72, 0xffff0000, v72
	v_lshlrev_b32_e32 v79, 16, v73
	v_and_b32_e32 v73, 0xffff0000, v73
	v_lshlrev_b32_e32 v80, 16, v74
	v_and_b32_e32 v74, 0xffff0000, v74
	v_mul_f32_e32 v67, v67, v75
	v_addc_co_u32_e32 v77, vcc, 0, v133, vcc
	v_add_co_u32_e32 v198, vcc, s79, v132
	s_nop 1
	v_addc_co_u32_e32 v199, vcc, 0, v133, vcc
	global_load_dwordx4 v[228:231], v[198:199], off offset:2304
	v_mul_f32_e32 v68, v68, v78
	v_mul_f32_e32 v69, v69, v72
	v_mul_f32_e32 v70, v70, v79
	v_mul_f32_e32 v71, v71, v73
	v_mul_f32_e32 v72, v64, v80
	v_mul_f32_e32 v73, v65, v74
	v_mul_f32_e32 v74, v66, v81
	v_cvt_pk_bf16_f32 v64, v68, v69
	v_cvt_pk_bf16_f32 v65, v70, v71
	v_cvt_pk_bf16_f32 v66, v72, v73
	v_cvt_pk_bf16_f32 v67, v74, v67
	flat_store_dwordx4 v[84:85], v[64:67] offset:256
	v_add_u32_e32 v68, 0x80, v128
	v_ashrrev_i32_e32 v69, 31, v68
	v_lshlrev_b64 v[68:69], 12, v[68:69]
	v_lshl_add_u64 v[68:69], s[10:11], 0, v[68:69]
	v_lshl_add_u64 v[68:69], v[68:69], 0, v[130:131]
	s_waitcnt vmcnt(13) lgkmcnt(0)
	s_nop 1
	v_mov_b32_e32 v64, v232
	v_mov_b32_e32 v65, v233
	v_mov_b32_e32 v66, v234
	v_mov_b32_e32 v67, v235
	v_add_co_u32_e32 v198, vcc, s79, v132
	s_nop 1
	v_addc_co_u32_e32 v199, vcc, 0, v133, vcc
	global_load_dwordx4 v[232:235], v[198:199], off offset:2816
	v_lshlrev_b32_e32 v73, 16, v67
	v_and_b32_e32 v67, 0xffff0000, v67
	v_lshlrev_b32_e32 v70, 16, v64
	v_and_b32_e32 v64, 0xffff0000, v64
	v_lshlrev_b32_e32 v71, 16, v65
	v_and_b32_e32 v65, 0xffff0000, v65
	v_lshlrev_b32_e32 v72, 16, v66
	v_and_b32_e32 v66, 0xffff0000, v66
	v_mul_f32_e32 v59, v59, v67
	v_mul_f32_e32 v60, v60, v70
	v_mul_f32_e32 v61, v61, v64
	v_mul_f32_e32 v62, v62, v71
	v_mul_f32_e32 v63, v63, v65
	v_mul_f32_e32 v64, v56, v72
	v_mul_f32_e32 v65, v57, v66
	v_mul_f32_e32 v66, v58, v73
	v_cvt_pk_bf16_f32 v56, v60, v61
	v_cvt_pk_bf16_f32 v57, v62, v63
	v_cvt_pk_bf16_f32 v58, v64, v65
	v_cvt_pk_bf16_f32 v59, v66, v59
	flat_store_dwordx4 v[68:69], v[56:59]
	v_add_co_u32_e32 v60, vcc, s75, v132
	s_waitcnt vmcnt(13) lgkmcnt(0)
	s_nop 1
	v_mov_b32_e32 v56, v236
	v_mov_b32_e32 v57, v237
	v_mov_b32_e32 v58, v238
	v_mov_b32_e32 v59, v239
	v_lshlrev_b32_e32 v65, 16, v59
	v_and_b32_e32 v59, 0xffff0000, v59
	v_lshlrev_b32_e32 v62, 16, v56
	v_and_b32_e32 v56, 0xffff0000, v56
	v_lshlrev_b32_e32 v63, 16, v57
	v_and_b32_e32 v57, 0xffff0000, v57
	v_lshlrev_b32_e32 v64, 16, v58
	v_and_b32_e32 v58, 0xffff0000, v58
	v_mul_f32_e32 v51, v51, v59
	v_addc_co_u32_e32 v61, vcc, 0, v133, vcc
	v_mul_f32_e32 v52, v52, v62
	v_mul_f32_e32 v53, v53, v56
	v_mul_f32_e32 v54, v54, v63
	v_mul_f32_e32 v55, v55, v57
	v_mul_f32_e32 v56, v48, v64
	v_mul_f32_e32 v57, v49, v58
	v_mul_f32_e32 v58, v50, v65
	v_cvt_pk_bf16_f32 v48, v52, v53
	v_cvt_pk_bf16_f32 v49, v54, v55
	v_cvt_pk_bf16_f32 v50, v56, v57
	v_cvt_pk_bf16_f32 v51, v58, v51
	flat_store_dwordx4 v[68:69], v[48:51] offset:256
	v_add_u32_e32 v52, 0x90, v128
	v_ashrrev_i32_e32 v53, 31, v52
	v_lshlrev_b64 v[52:53], 12, v[52:53]
	v_lshl_add_u64 v[52:53], s[10:11], 0, v[52:53]
	v_lshl_add_u64 v[52:53], v[52:53], 0, v[130:131]
	s_waitcnt vmcnt(12) lgkmcnt(0)
	s_nop 1
	v_mov_b32_e32 v48, v240
	v_mov_b32_e32 v49, v241
	v_mov_b32_e32 v50, v242
	v_mov_b32_e32 v51, v243
	v_lshlrev_b32_e32 v57, 16, v51
	v_and_b32_e32 v51, 0xffff0000, v51
	v_lshlrev_b32_e32 v54, 16, v48
	v_and_b32_e32 v48, 0xffff0000, v48
	v_lshlrev_b32_e32 v55, 16, v49
	v_and_b32_e32 v49, 0xffff0000, v49
	v_lshlrev_b32_e32 v56, 16, v50
	v_and_b32_e32 v50, 0xffff0000, v50
	v_mul_f32_e32 v43, v43, v51
	v_mul_f32_e32 v44, v44, v54
	v_mul_f32_e32 v45, v45, v48
	v_mul_f32_e32 v46, v46, v55
	v_mul_f32_e32 v47, v47, v49
	v_mul_f32_e32 v48, v40, v56
	v_mul_f32_e32 v49, v41, v50
	v_mul_f32_e32 v50, v42, v57
	v_cvt_pk_bf16_f32 v40, v44, v45
	v_cvt_pk_bf16_f32 v41, v46, v47
	v_cvt_pk_bf16_f32 v42, v48, v49
	v_cvt_pk_bf16_f32 v43, v50, v43
	flat_store_dwordx4 v[52:53], v[40:43]
	v_add_co_u32_e32 v44, vcc, s76, v132
	s_waitcnt vmcnt(11) lgkmcnt(0)
	s_nop 1
	v_mov_b32_e32 v40, v244
	v_mov_b32_e32 v41, v245
	v_mov_b32_e32 v42, v246
	v_mov_b32_e32 v43, v247
	v_lshlrev_b32_e32 v49, 16, v43
	v_and_b32_e32 v43, 0xffff0000, v43
	v_lshlrev_b32_e32 v46, 16, v40
	v_and_b32_e32 v40, 0xffff0000, v40
	v_lshlrev_b32_e32 v47, 16, v41
	v_and_b32_e32 v41, 0xffff0000, v41
	v_lshlrev_b32_e32 v48, 16, v42
	v_and_b32_e32 v42, 0xffff0000, v42
	v_mul_f32_e32 v35, v35, v43
	v_addc_co_u32_e32 v45, vcc, 0, v133, vcc
	v_mul_f32_e32 v36, v36, v46
	v_mul_f32_e32 v37, v37, v40
	v_mul_f32_e32 v38, v38, v47
	v_mul_f32_e32 v39, v39, v41
	v_mul_f32_e32 v40, v32, v48
	v_mul_f32_e32 v41, v33, v42
	v_mul_f32_e32 v42, v34, v49
	v_cvt_pk_bf16_f32 v32, v36, v37
	v_cvt_pk_bf16_f32 v33, v38, v39
	v_cvt_pk_bf16_f32 v34, v40, v41
	v_cvt_pk_bf16_f32 v35, v42, v35
	flat_store_dwordx4 v[52:53], v[32:35] offset:256
	v_add_u32_e32 v36, 0xa0, v128
	v_ashrrev_i32_e32 v37, 31, v36
	v_lshlrev_b64 v[36:37], 12, v[36:37]
	v_lshl_add_u64 v[36:37], s[10:11], 0, v[36:37]
	v_lshl_add_u64 v[36:37], v[36:37], 0, v[130:131]
	s_waitcnt vmcnt(10) lgkmcnt(0)
	s_nop 1
	v_mov_b32_e32 v32, v248
	v_mov_b32_e32 v33, v249
	v_mov_b32_e32 v34, v250
	v_mov_b32_e32 v35, v251
	v_lshlrev_b32_e32 v41, 16, v35
	v_and_b32_e32 v35, 0xffff0000, v35
	v_lshlrev_b32_e32 v38, 16, v32
	v_and_b32_e32 v32, 0xffff0000, v32
	v_lshlrev_b32_e32 v39, 16, v33
	v_and_b32_e32 v33, 0xffff0000, v33
	v_lshlrev_b32_e32 v40, 16, v34
	v_and_b32_e32 v34, 0xffff0000, v34
	v_mul_f32_e32 v27, v27, v35
	v_mul_f32_e32 v28, v28, v38
	v_mul_f32_e32 v29, v29, v32
	v_mul_f32_e32 v30, v30, v39
	v_mul_f32_e32 v31, v31, v33
	v_mul_f32_e32 v32, v24, v40
	v_mul_f32_e32 v33, v25, v34
	v_mul_f32_e32 v34, v26, v41
	v_cvt_pk_bf16_f32 v24, v28, v29
	v_cvt_pk_bf16_f32 v25, v30, v31
	v_cvt_pk_bf16_f32 v26, v32, v33
	v_cvt_pk_bf16_f32 v27, v34, v27
	flat_store_dwordx4 v[36:37], v[24:27]
	v_add_co_u32_e32 v28, vcc, s79, v132
	s_waitcnt vmcnt(9) lgkmcnt(0)
	s_nop 1
	v_mov_b32_e32 v24, v252
	v_mov_b32_e32 v25, v253
	v_mov_b32_e32 v26, v254
	v_mov_b32_e32 v27, v255
	v_lshlrev_b32_e32 v33, 16, v27
	v_and_b32_e32 v27, 0xffff0000, v27
	v_lshlrev_b32_e32 v30, 16, v24
	v_and_b32_e32 v24, 0xffff0000, v24
	v_lshlrev_b32_e32 v31, 16, v25
	v_and_b32_e32 v25, 0xffff0000, v25
	v_lshlrev_b32_e32 v32, 16, v26
	v_and_b32_e32 v26, 0xffff0000, v26
	v_mul_f32_e32 v19, v19, v27
	v_addc_co_u32_e32 v29, vcc, 0, v133, vcc
	v_mul_f32_e32 v20, v20, v30
	v_mul_f32_e32 v21, v21, v24
	v_mul_f32_e32 v22, v22, v31
	v_mul_f32_e32 v23, v23, v25
	v_mul_f32_e32 v24, v16, v32
	v_mul_f32_e32 v25, v17, v26
	v_mul_f32_e32 v26, v18, v33
	v_cvt_pk_bf16_f32 v16, v20, v21
	v_cvt_pk_bf16_f32 v17, v22, v23
	v_cvt_pk_bf16_f32 v18, v24, v25
	v_cvt_pk_bf16_f32 v19, v26, v19
	flat_store_dwordx4 v[36:37], v[16:19] offset:256
	v_add_u32_e32 v20, 0xb0, v128
	v_ashrrev_i32_e32 v21, 31, v20
	v_lshlrev_b64 v[20:21], 12, v[20:21]
	v_lshl_add_u64 v[20:21], s[10:11], 0, v[20:21]
	v_lshl_add_u64 v[20:21], v[20:21], 0, v[130:131]
	s_andn2_b64 vcc, exec, s[50:51]
	s_mov_b64 s[50:51], -1
	s_waitcnt vmcnt(8) lgkmcnt(0)
	s_nop 1
	v_mov_b32_e32 v16, v228
	v_mov_b32_e32 v17, v229
	v_mov_b32_e32 v18, v230
	v_mov_b32_e32 v19, v231
	v_lshlrev_b32_e32 v25, 16, v19
	v_and_b32_e32 v19, 0xffff0000, v19
	v_lshlrev_b32_e32 v22, 16, v16
	v_and_b32_e32 v16, 0xffff0000, v16
	v_lshlrev_b32_e32 v23, 16, v17
	v_and_b32_e32 v17, 0xffff0000, v17
	v_lshlrev_b32_e32 v24, 16, v18
	v_and_b32_e32 v18, 0xffff0000, v18
	v_mul_f32_e32 v11, v11, v19
	v_mul_f32_e32 v12, v12, v22
	v_mul_f32_e32 v13, v13, v16
	v_mul_f32_e32 v14, v14, v23
	v_mul_f32_e32 v15, v15, v17
	v_mul_f32_e32 v16, v8, v24
	v_mul_f32_e32 v17, v9, v18
	v_mul_f32_e32 v18, v10, v25
	v_cvt_pk_bf16_f32 v8, v12, v13
	v_cvt_pk_bf16_f32 v9, v14, v15
	v_cvt_pk_bf16_f32 v10, v16, v17
	v_cvt_pk_bf16_f32 v11, v18, v11
	flat_store_dwordx4 v[20:21], v[8:11]
	s_waitcnt vmcnt(7) lgkmcnt(0)
	s_nop 1
	v_mov_b32_e32 v8, v232
	v_mov_b32_e32 v9, v233
	v_mov_b32_e32 v10, v234
	v_mov_b32_e32 v11, v235
	v_lshlrev_b32_e32 v15, 16, v11
	v_and_b32_e32 v11, 0xffff0000, v11
	v_lshlrev_b32_e32 v12, 16, v8
	v_and_b32_e32 v8, 0xffff0000, v8
	v_lshlrev_b32_e32 v13, 16, v9
	v_and_b32_e32 v9, 0xffff0000, v9
	v_lshlrev_b32_e32 v14, 16, v10
	v_and_b32_e32 v10, 0xffff0000, v10
	v_mul_f32_e32 v3, v3, v11
	v_mul_f32_e32 v4, v4, v12
	v_mul_f32_e32 v5, v5, v8
	v_mul_f32_e32 v6, v6, v13
	v_mul_f32_e32 v7, v7, v9
	v_mul_f32_e32 v8, v0, v14
	v_mul_f32_e32 v9, v1, v10
	v_mul_f32_e32 v10, v2, v15
	v_cvt_pk_bf16_f32 v0, v4, v5
	v_cvt_pk_bf16_f32 v1, v6, v7
	v_cvt_pk_bf16_f32 v2, v8, v9
	v_cvt_pk_bf16_f32 v3, v10, v3
	flat_store_dwordx4 v[20:21], v[0:3] offset:256
	s_cbranch_vccnz .LBB0_436
	s_andn2_b64 vcc, exec, s[6:7]
	s_cbranch_vccnz .LBB0_435
	s_barrier
	s_branch .LBB0_435
